# seam 9 moved inside P10's work loop: each workgroup first takes one of 192 memory-attention items (independent of P9) from a second counter, then the grid barrier, then the normal queue
# speedup vs baseline: 1.0026x; 1.0026x over previous
.LBB0_1163:
	s_cmp_gt_i32 s45, 10
	s_cselect_b64 s[6:7], -1, 0
	s_and_b64 s[8:9], s[10:11], s[6:7]
	s_andn2_b64 vcc, exec, s[8:9]
	s_mov_b32 s101, 0
	s_cbranch_vccnz .LBB0_1218
	s_movk_i32 s101, 0x101
	s_branch .LBB0_1218
.Lseam9_entry:
	s_waitcnt vmcnt(0)
	s_waitcnt vmcnt(0) lgkmcnt(0)
	s_barrier
	s_and_saveexec_b64 s[8:9], s[4:5]
	s_cbranch_execz .Lseam9_aux
	s_add_i32 s3, 0, 0x20000
	v_mov_b32_e32 v0, s3
	s_waitcnt vmcnt(0) expcnt(0) lgkmcnt(0)
	ds_read_b32 v2, v0
	s_add_i32 s3, 0, 0x20004
	v_mov_b32_e32 v0, s3
	ds_read_b32 v0, v0
	s_waitcnt lgkmcnt(1)
	v_cmp_ne_u32_e32 vcc, 0, v2
	s_cbranch_vccnz .LBB0_1180
	s_add_u32 s10, s42, 0x1000
	s_addc_u32 s11, s43, 0
	s_add_u32 s12, s42, 0x1100
	s_load_dword s3, s[0:1], 0xe8
	s_addc_u32 s13, s43, 0
	s_add_u32 s14, s42, 0x1200
	s_addc_u32 s15, s43, 0
	s_add_u32 s16, s42, 0x1300
	s_addc_u32 s17, s43, 0
	s_waitcnt lgkmcnt(0)
	s_mul_i32 s3, s47, s3
	s_add_u32 s18, s42, 0x1400
	s_mul_i32 s3, s3, s46
	s_addc_u32 s19, s43, 0
	s_mov_b32 s26, 1
	v_mov_b32_e32 v16, 0
	s_branch .LBB0_1168

.LBB0_1217:
	s_or_b64 exec, exec, s[8:9]
	s_waitcnt lgkmcnt(0)
	s_barrier
	s_branch .Lp10_seam_ret

.LBB0_1223:
	s_and_saveexec_b64 s[6:7], s[4:5]
	s_cbranch_execz .LBB0_1227
	s_mov_b64 s[10:11], exec
	v_mbcnt_lo_u32_b32 v0, s10, 0
	v_mbcnt_hi_u32_b32 v0, s11, v0
	v_cmp_eq_u32_e32 vcc, 0, v0
	s_and_saveexec_b64 s[8:9], vcc
	s_cbranch_execz .LBB0_1226
	s_bcnt1_i32_b64 s10, s[10:11]
	v_mov_b32_e32 v1, s10
	s_cmp_lg_u32 s100, 0
	s_cbranch_scc1 .Lpop_pref
	s_cmpk_eq_u32 s101, 0x101
	s_cselect_b32 s98, 32, 0
	v_mov_b32_e32 v2, s98
	global_atomic_add v1, v2, v1, s[42:43] sc0
	s_branch .LBB0_1226

.LBB0_1226:
	s_or_b64 exec, exec, s[8:9]
	s_mov_b32 s100, 0
	s_waitcnt vmcnt(0)
	v_readfirstlane_b32 s8, v1
	s_cmp_eq_u32 s101, 0
	s_cbranch_scc1 .Lmf_done
	s_cmpk_eq_u32 s101, 0x101
	s_cbranch_scc0 .Lmf_main
	s_cmp_lt_u32 s8, 0xc0
	s_cbranch_scc1 .Lmf_mem0
	s_movk_i32 s8, 0x400
	s_branch .Lmf_done
.Lmf_mem0:
	s_add_u32 s8, s8, 0x300
	s_branch .Lmf_done
.Lmf_main:
	s_cmp_lt_u32 s8, 0x300
	s_cbranch_scc1 .Lmf_done
	s_cmp_lt_u32 s8, 0x340
	s_cbranch_scc1 .Lmf_mem1
	s_movk_i32 s8, 0x400
	s_branch .Lmf_done
.Lmf_mem1:
	s_add_u32 s8, s8, 0xc0

.LBB0_1227:
	s_or_b64 exec, exec, s[6:7]
	s_waitcnt vmcnt(0) lgkmcnt(0)
	s_barrier
	ds_read_b32 v0, v236
	s_mov_b64 s[6:7], -1
	s_waitcnt lgkmcnt(0)
	s_barrier
	v_readfirstlane_b32 s84, v0
	s_cmpk_eq_u32 s101, 0x101
	s_cbranch_scc0 .Lp10_not_first
	s_movk_i32 s101, 0x102
	s_cmpk_lt_u32 s84, 0x400
	s_cbranch_scc1 .Lp10_go
	s_movk_i32 s84, 0x7fff
	s_branch .Lp10_do_seam
.Lp10_not_first:
	s_cmpk_eq_u32 s101, 0x102
	s_cbranch_scc0 .Lp10_go
.Lp10_do_seam:
	s_mov_b32 s99, s3
	s_branch .Lseam9_entry
.Lp10_seam_ret:
	s_mov_b32 s3, s99
	s_movk_i32 s101, 0x100
	s_cmpk_eq_u32 s84, 0x7fff
	s_cbranch_scc1 .LBB0_1223
.Lp10_go:
	s_cmpk_gt_u32 s84, 0x3ff
	s_cbranch_scc1 .LBB0_1222
	s_cmpk_gt_u32 s84, 0x2ff
	s_cbranch_scc0 .LBB0_1285
	s_add_i32 s6, s84, 0xfffffd00
	s_lshr_b32 s24, s6, 6
	s_lshl_b32 s7, s6, 8
	s_lshl_b64 s[38:39], s[24:25], 12
	s_and_b32 s7, s7, 0xf00
	s_or_b32 s38, s38, s7
	s_mul_hi_u32 s8, s38, 0x1e00
	s_mul_i32 s9, s39, 0x1e00
	s_mul_i32 s7, s38, 0x1e00
	s_add_i32 s8, s8, s9
	s_add_u32 s85, s61, s7
	s_addc_u32 s86, s62, s8
	s_lshl_b32 s6, s6, 3
	s_and_b32 s6, s6, 0x180
	s_lshl_b32 s87, s6, 1
	s_add_u32 s7, s85, s87
	s_addc_u32 s9, s86, 0
	s_add_u32 s8, s7, 0x1000
	s_addc_u32 s9, s9, 0
	s_lshl_b32 s24, s24, 8
	s_lshl_b64 s[10:11], s[24:25], 10
	s_add_u32 s7, s65, s10
	s_addc_u32 s10, s66, s11
	s_add_u32 s50, s7, s87
	v_readfirstlane_b32 s54, v213
	s_addc_u32 s51, s10, 0
	s_lshr_b32 s90, s54, 6
	s_lshl_b32 s82, s90, 5
	v_or_b32_e32 v180, s82, v212
	v_mov_b64_e32 v[0:1], s[8:9]
	v_mad_u64_u32 v[0:1], s[8:9], v180, s72, v[0:1]
	v_mov_b32_e32 v153, v145
	v_lshl_add_u64 v[0:1], v[0:1], 0, v[152:153]
	global_load_dwordx4 v[124:127], v[0:1], off
	global_load_dwordx4 v[120:123], v[0:1], off offset:32
	global_load_dwordx4 v[116:119], v[0:1], off offset:64
	global_load_dwordx4 v[112:115], v[0:1], off offset:96
	global_load_dwordx4 v[108:111], v[0:1], off offset:128
	global_load_dwordx4 v[104:107], v[0:1], off offset:160
	global_load_dwordx4 v[100:103], v[0:1], off offset:192
	global_load_dwordx4 v[96:99], v[0:1], off offset:224
	s_lshl_b32 s88, s90, 10
	v_or_b32_e32 v0, s88, v147
	v_mul_hi_i32 v1, v0, s74
	v_lshrrev_b32_e32 v2, 31, v1
	v_ashrrev_i32_e32 v1, 7, v1
	v_add_u32_e32 v1, v1, v2
	v_mul_i32_i24_e32 v2, 0x110, v1
	v_sub_u32_e32 v2, v0, v2
	v_cmp_gt_i32_e32 vcc, s75, v2
	v_min_i32_e32 v1, 63, v1
	s_cmpk_lt_u32 s54, 0x440
	v_cndmask_b32_e32 v2, 0, v2, vcc
	s_cselect_b64 s[8:9], -1, 0
	s_cmpk_gt_u32 s54, 0x43f
	v_lshl_add_u32 v144, v1, 10, v2
	s_cbranch_scc1 .LBB0_1231
	s_add_i32 m0, s88, 0
	s_nop 0
	global_load_lds_dwordx4 v144, s[50:51]
